# scan waves run at s_setprio 3
# speedup vs baseline: 1.0139x; 1.0046x over previous
.LBB0_399:
	s_setprio 0
	v_mov_b32_e32 v1, v198
	s_waitcnt lgkmcnt(0)
	s_barrier
	s_nop 0
	v_cmp_eq_u32_e32 vcc, 0, v1
	s_and_saveexec_b64 s[0:1], vcc
	s_cbranch_execz .LBB0_401
	v_mov_b64_e32 v[4:5], s[14:15]
	flat_atomic_add v1, v[4:5], v199 sc0
	v_mov_b32_e32 v2, s2
	s_waitcnt vmcnt(0) lgkmcnt(0)
	ds_write_b32 v2, v1

.LBB0_487:
	s_and_b64 vcc, exec, s[0:1]
	s_cbranch_vccz .LBB0_397
	s_setprio 3
	v_mov_b64_e32 v[4:5], s[16:17]
	flat_load_dwordx2 v[100:101], v[4:5]
	s_lshl_b32 s4, s75, 6
	s_and_b32 s0, s75, 1
	s_ashr_i32 s1, s75, 3
	s_and_b32 s4, s4, 0xffffff80
	s_ashr_i32 s5, s4, 31
	s_mul_i32 s8, s1, 0x3800000
	s_lshl_b32 s9, s0, 7
	s_lshl_b32 s18, s0, 13
	s_lshl_b32 s10, s75, 7
	s_and_b32 s10, s10, 0x300
	s_add_i32 s8, s8, s9
	s_add_i32 s8, s8, s10
	v_and_b32_e32 v22, 63, v198
	v_mov_b32_e32 v23, 0
	v_lshrrev_b32_e32 v24, 6, v198
	v_mov_b32_e32 v25, 0
	v_and_b32_e32 v26, 15, v198
	v_bfe_u32 v27, v198, 4, 2
	v_lshl_add_u32 v2, v22, 4, 0
	v_lshlrev_b32_e32 v131, 11, v24
	v_lshl_add_u32 v131, v22, 3, v131
	v_mul_u32_u24_e32 v114, 0x7000, v27
	v_lshl_add_u32 v114, v24, 5, v114
	v_lshl_add_u32 v114, v26, 1, v114
	v_add_u32_e32 v114, s8, v114
	s_nop 0
	v_readfirstlane_b32 s93, v24
	s_mov_b64 s[94:95], 0x4000
	s_mov_b64 s[96:97], 0x8000
	s_mov_b64 s[78:79], 0x400
	s_mov_b64 s[98:99], 0x800
	s_mov_b64 s[100:101], 0xc00
	s_lshl_b32 s88, s93, 12
	s_add_i32 s89, s88, 0x4000
	s_add_i32 s90, s88, 0x8000
	s_lshl_b32 s91, s93, 11
	s_add_i32 s92, s91, 0xe000
	s_add_i32 s91, s91, 0xc000
	s_lshl_b64 s[0:1], s[4:5], 2
	s_add_u32 s0, s0, 0x2ce00000
	s_addc_u32 s1, s1, 0
	s_movk_i32 s6, 0x7f
	v_mov_b32_e32 v4, 0
	v_mov_b32_e32 v5, v4
	v_mov_b32_e32 v6, v4
	v_mov_b32_e32 v7, v4
	v_mov_b32_e32 v16, v4
	v_mov_b32_e32 v17, v4
	v_mov_b32_e32 v18, v4
	v_mov_b32_e32 v19, v4
	v_mov_b32_e32 v44, v4
	v_mov_b32_e32 v45, v4
	v_mov_b32_e32 v46, v4
	v_mov_b32_e32 v47, v4
	v_mov_b32_e32 v76, v4
	v_mov_b32_e32 v77, v4
	v_mov_b32_e32 v78, v4
	v_mov_b32_e32 v79, v4
	v_mov_b32_e32 v84, v4
	v_mov_b32_e32 v85, v4
	v_mov_b32_e32 v86, v4
	v_mov_b32_e32 v87, v4
	v_mov_b32_e32 v88, v4
	v_mov_b32_e32 v89, v4
	v_mov_b32_e32 v90, v4
	v_mov_b32_e32 v91, v4
	v_mov_b32_e32 v92, v4
	v_mov_b32_e32 v93, v4
	v_mov_b32_e32 v94, v4
	v_mov_b32_e32 v95, v4
	v_mov_b32_e32 v96, v4
	v_mov_b32_e32 v97, v4
	v_mov_b32_e32 v98, v4
	v_mov_b32_e32 v99, v4
	s_waitcnt vmcnt(0) lgkmcnt(0)
	v_readfirstlane_b32 s86, v100
	v_readfirstlane_b32 s87, v101
	v_mad_i64_i32 v[28:29], s[10:11], s4, v210, v[100:101]
	v_lshl_add_u64 v[28:29], v[28:29], 0, s[34:35]
	v_lshl_add_u64 v[28:29], v[22:23], 4, v[28:29]
	v_lshlrev_b32_e32 v32, 12, v24
	v_mov_b32_e32 v33, 0
	v_lshl_add_u64 v[8:9], v[32:33], 0, v[28:29]
	v_lshl_add_u64 v[10:11], v[8:9], 0, s[94:95]
	v_lshl_add_u64 v[12:13], v[8:9], 0, s[96:97]
	v_lshlrev_b32_e32 v32, 11, v24
	v_lshl_add_u64 v[14:15], v[32:33], 0, v[28:29]
	s_add_u32 s10, s18, 0xe000
	s_mov_b32 s11, 0
	v_lshl_add_u64 v[20:21], v[14:15], 0, s[10:11]
	s_mov_b64 s[10:11], 0xc000
	v_lshl_add_u64 v[14:15], v[14:15], 0, s[10:11]
	v_lshl_add_u64 v[32:33], v[100:101], 0, s[0:1]
	v_lshl_add_u64 v[32:33], v[22:23], 2, v[32:33]
	global_load_dword v34, v[32:33], off
	global_load_dword v35, v[32:33], off offset:256
	s_mov_b32 m0, s88
	s_nop 0
	global_load_lds_dwordx4 v[8:9], off
	s_add_i32 m0, s88, 0x400
	v_lshl_add_u64 v[30:31], v[8:9], 0, s[78:79]
	global_load_lds_dwordx4 v[30:31], off
	s_add_i32 m0, s88, 0x800
	v_lshl_add_u64 v[30:31], v[8:9], 0, s[98:99]
	global_load_lds_dwordx4 v[30:31], off
	s_add_i32 m0, s88, 0xc00
	v_lshl_add_u64 v[30:31], v[8:9], 0, s[100:101]
	global_load_lds_dwordx4 v[30:31], off
	s_mov_b32 m0, s92
	s_nop 0
	global_load_lds_dwordx4 v[20:21], off
	s_add_i32 m0, s92, 0x400
	v_lshl_add_u64 v[30:31], v[20:21], 0, s[78:79]
	global_load_lds_dwordx4 v[30:31], off
	s_mov_b32 m0, s89
	s_nop 0
	global_load_lds_dwordx4 v[10:11], off
	s_add_i32 m0, s89, 0x400
	v_lshl_add_u64 v[30:31], v[10:11], 0, s[78:79]
	global_load_lds_dwordx4 v[30:31], off
	s_add_i32 m0, s89, 0x800
	v_lshl_add_u64 v[30:31], v[10:11], 0, s[98:99]
	global_load_lds_dwordx4 v[30:31], off
	s_add_i32 m0, s89, 0xc00
	v_lshl_add_u64 v[30:31], v[10:11], 0, s[100:101]
	global_load_lds_dwordx4 v[30:31], off
	s_mov_b32 m0, s91
	s_nop 0
	global_load_lds_dwordx4 v[14:15], off
	s_add_i32 m0, s91, 0x400
	v_lshl_add_u64 v[30:31], v[14:15], 0, s[78:79]
	global_load_lds_dwordx4 v[30:31], off
	s_mov_b32 m0, s90
	s_nop 0
	global_load_lds_dwordx4 v[12:13], off
	s_add_i32 m0, s90, 0x400
	v_lshl_add_u64 v[30:31], v[12:13], 0, s[78:79]
	global_load_lds_dwordx4 v[30:31], off
	s_add_i32 m0, s90, 0x800
	v_lshl_add_u64 v[30:31], v[12:13], 0, s[98:99]
	global_load_lds_dwordx4 v[30:31], off
	s_add_i32 m0, s90, 0xc00
	v_lshl_add_u64 v[30:31], v[12:13], 0, s[100:101]
	global_load_lds_dwordx4 v[30:31], off
	v_lshl_add_u64 v[8:9], v[8:9], 0, s[50:51]
	v_lshl_add_u64 v[10:11], v[10:11], 0, s[50:51]
	v_lshl_add_u64 v[12:13], v[12:13], 0, s[50:51]
	v_lshl_add_u64 v[14:15], v[14:15], 0, s[50:51]
	v_lshl_add_u64 v[20:21], v[20:21], 0, s[50:51]
	s_waitcnt vmcnt(0)
	s_barrier
